# GEMM phase prologues: second staging batch issued before the first wait; P0a: silu(c) staging loads issued together (32 per thread) instead of one per trip
# baseline (speedup 1.0000x reference)
.LBB0_131:
	s_or_b64 exec, exec, s[4:5]
	s_cmpk_gt_u32 s87, 0x8f
	s_waitcnt lgkmcnt(0)
	s_barrier
	s_cbranch_scc1 .LBB0_142
	s_load_dwordx4 s[4:7], s[14:15], 0x18
	s_movk_i32 s2, 0x4000
	v_cmp_gt_i32_e32 vcc, s2, v82
	s_and_saveexec_b64 s[8:9], vcc
	s_cbranch_execz .LBB0_135
	s_load_dwordx2 s[2:3], s[14:15], 0x8
	v_ashrrev_i32_e32 v83, 31, v82
	v_lshlrev_b32_e32 v1, 4, v82
	s_mov_b64 s[10:11], 0
	s_mov_b64 s[14:15], 0x800
	s_waitcnt lgkmcnt(0)
	v_lshl_add_u64 v[2:3], v[82:83], 2, s[2:3]
	s_movk_i32 s2, 0x3dff
	v_mov_b32_e32 v4, v82
	v_mov_b32_e32 v164, v2
	v_mov_b32_e32 v165, v3
	v_lshlrev_b32_e32 v198, 6, v82
	s_mov_b64 s[14:15], 0x1000
	global_load_dword v166, v[164:165], off
	global_load_dword v167, v[164:165], off offset:2048
	v_lshl_add_u64 v[164:165], v[164:165], 0, s[14:15]
	global_load_dword v168, v[164:165], off
	global_load_dword v169, v[164:165], off offset:2048
	v_lshl_add_u64 v[164:165], v[164:165], 0, s[14:15]
	global_load_dword v170, v[164:165], off
	global_load_dword v171, v[164:165], off offset:2048
	v_lshl_add_u64 v[164:165], v[164:165], 0, s[14:15]
	global_load_dword v172, v[164:165], off
	global_load_dword v173, v[164:165], off offset:2048
	v_lshl_add_u64 v[164:165], v[164:165], 0, s[14:15]
	global_load_dword v174, v[164:165], off
	global_load_dword v175, v[164:165], off offset:2048
	v_lshl_add_u64 v[164:165], v[164:165], 0, s[14:15]
	global_load_dword v176, v[164:165], off
	global_load_dword v177, v[164:165], off offset:2048
	v_lshl_add_u64 v[164:165], v[164:165], 0, s[14:15]
	global_load_dword v178, v[164:165], off
	global_load_dword v179, v[164:165], off offset:2048
	v_lshl_add_u64 v[164:165], v[164:165], 0, s[14:15]
	global_load_dword v180, v[164:165], off
	global_load_dword v181, v[164:165], off offset:2048
	v_lshl_add_u64 v[164:165], v[164:165], 0, s[14:15]
	global_load_dword v182, v[164:165], off
	global_load_dword v183, v[164:165], off offset:2048
	v_lshl_add_u64 v[164:165], v[164:165], 0, s[14:15]
	global_load_dword v184, v[164:165], off
	global_load_dword v185, v[164:165], off offset:2048
	v_lshl_add_u64 v[164:165], v[164:165], 0, s[14:15]
	global_load_dword v186, v[164:165], off
	global_load_dword v187, v[164:165], off offset:2048
	v_lshl_add_u64 v[164:165], v[164:165], 0, s[14:15]
	global_load_dword v188, v[164:165], off
	global_load_dword v189, v[164:165], off offset:2048
	v_lshl_add_u64 v[164:165], v[164:165], 0, s[14:15]
	global_load_dword v190, v[164:165], off
	global_load_dword v191, v[164:165], off offset:2048
	v_lshl_add_u64 v[164:165], v[164:165], 0, s[14:15]
	global_load_dword v192, v[164:165], off
	global_load_dword v193, v[164:165], off offset:2048
	v_lshl_add_u64 v[164:165], v[164:165], 0, s[14:15]
	global_load_dword v194, v[164:165], off
	global_load_dword v195, v[164:165], off offset:2048
	v_lshl_add_u64 v[164:165], v[164:165], 0, s[14:15]
	global_load_dword v196, v[164:165], off
	global_load_dword v197, v[164:165], off offset:2048
	s_waitcnt vmcnt(24)
	v_mul_f32_e32 v200, 0xbfb8aa3b, v166
	v_mul_f32_e32 v201, 0xbfb8aa3b, v167
	v_mul_f32_e32 v202, 0xbfb8aa3b, v168
	v_mul_f32_e32 v203, 0xbfb8aa3b, v169
	v_mul_f32_e32 v204, 0xbfb8aa3b, v170
	v_mul_f32_e32 v205, 0xbfb8aa3b, v171
	v_mul_f32_e32 v206, 0xbfb8aa3b, v172
	v_mul_f32_e32 v207, 0xbfb8aa3b, v173
	v_exp_f32_e32 v200, v200
	v_exp_f32_e32 v201, v201
	v_exp_f32_e32 v202, v202
	v_exp_f32_e32 v203, v203
	v_exp_f32_e32 v204, v204
	v_exp_f32_e32 v205, v205
	v_exp_f32_e32 v206, v206
	v_exp_f32_e32 v207, v207
	s_nop 0
	v_add_f32_e32 v200, 1.0, v200
	v_add_f32_e32 v201, 1.0, v201
	v_add_f32_e32 v202, 1.0, v202
	v_add_f32_e32 v203, 1.0, v203
	v_add_f32_e32 v204, 1.0, v204
	v_add_f32_e32 v205, 1.0, v205
	v_add_f32_e32 v206, 1.0, v206
	v_add_f32_e32 v207, 1.0, v207
	v_rcp_f32_e32 v200, v200
	v_rcp_f32_e32 v201, v201
	v_rcp_f32_e32 v202, v202
	v_rcp_f32_e32 v203, v203
	v_rcp_f32_e32 v204, v204
	v_rcp_f32_e32 v205, v205
	v_rcp_f32_e32 v206, v206
	v_rcp_f32_e32 v207, v207
	s_nop 0
	v_mul_f32_e32 v166, v166, v200
	v_mul_f32_e32 v167, v167, v201
	v_mul_f32_e32 v168, v168, v202
	v_mul_f32_e32 v169, v169, v203
	v_mul_f32_e32 v170, v170, v204
	v_mul_f32_e32 v171, v171, v205
	v_mul_f32_e32 v172, v172, v206
	v_mul_f32_e32 v173, v173, v207
	ds_write_b32 v198, v166
	ds_write_b32 v198, v167 offset:32768
	ds_write_b32 v198, v168 offset:4
	ds_write_b32 v198, v169 offset:32772
	ds_write_b32 v198, v170 offset:8
	ds_write_b32 v198, v171 offset:32776
	ds_write_b32 v198, v172 offset:12
	ds_write_b32 v198, v173 offset:32780
	s_waitcnt vmcnt(16)
	v_mul_f32_e32 v200, 0xbfb8aa3b, v174
	v_mul_f32_e32 v201, 0xbfb8aa3b, v175
	v_mul_f32_e32 v202, 0xbfb8aa3b, v176
	v_mul_f32_e32 v203, 0xbfb8aa3b, v177
	v_mul_f32_e32 v204, 0xbfb8aa3b, v178
	v_mul_f32_e32 v205, 0xbfb8aa3b, v179
	v_mul_f32_e32 v206, 0xbfb8aa3b, v180
	v_mul_f32_e32 v207, 0xbfb8aa3b, v181
	v_exp_f32_e32 v200, v200
	v_exp_f32_e32 v201, v201
	v_exp_f32_e32 v202, v202
	v_exp_f32_e32 v203, v203
	v_exp_f32_e32 v204, v204
	v_exp_f32_e32 v205, v205
	v_exp_f32_e32 v206, v206
	v_exp_f32_e32 v207, v207
	s_nop 0
	v_add_f32_e32 v200, 1.0, v200
	v_add_f32_e32 v201, 1.0, v201
	v_add_f32_e32 v202, 1.0, v202
	v_add_f32_e32 v203, 1.0, v203
	v_add_f32_e32 v204, 1.0, v204
	v_add_f32_e32 v205, 1.0, v205
	v_add_f32_e32 v206, 1.0, v206
	v_add_f32_e32 v207, 1.0, v207
	v_rcp_f32_e32 v200, v200
	v_rcp_f32_e32 v201, v201
	v_rcp_f32_e32 v202, v202
	v_rcp_f32_e32 v203, v203
	v_rcp_f32_e32 v204, v204
	v_rcp_f32_e32 v205, v205
	v_rcp_f32_e32 v206, v206
	v_rcp_f32_e32 v207, v207
	s_nop 0
	v_mul_f32_e32 v174, v174, v200
	v_mul_f32_e32 v175, v175, v201
	v_mul_f32_e32 v176, v176, v202
	v_mul_f32_e32 v177, v177, v203
	v_mul_f32_e32 v178, v178, v204
	v_mul_f32_e32 v179, v179, v205
	v_mul_f32_e32 v180, v180, v206
	v_mul_f32_e32 v181, v181, v207
	ds_write_b32 v198, v174 offset:16
	ds_write_b32 v198, v175 offset:32784
	ds_write_b32 v198, v176 offset:20
	ds_write_b32 v198, v177 offset:32788
	ds_write_b32 v198, v178 offset:24
	ds_write_b32 v198, v179 offset:32792
	ds_write_b32 v198, v180 offset:28
	ds_write_b32 v198, v181 offset:32796
	s_waitcnt vmcnt(8)
	v_mul_f32_e32 v200, 0xbfb8aa3b, v182
	v_mul_f32_e32 v201, 0xbfb8aa3b, v183
	v_mul_f32_e32 v202, 0xbfb8aa3b, v184
	v_mul_f32_e32 v203, 0xbfb8aa3b, v185
	v_mul_f32_e32 v204, 0xbfb8aa3b, v186
	v_mul_f32_e32 v205, 0xbfb8aa3b, v187
	v_mul_f32_e32 v206, 0xbfb8aa3b, v188
	v_mul_f32_e32 v207, 0xbfb8aa3b, v189
	v_exp_f32_e32 v200, v200
	v_exp_f32_e32 v201, v201
	v_exp_f32_e32 v202, v202
	v_exp_f32_e32 v203, v203
	v_exp_f32_e32 v204, v204
	v_exp_f32_e32 v205, v205
	v_exp_f32_e32 v206, v206
	v_exp_f32_e32 v207, v207
	s_nop 0
	v_add_f32_e32 v200, 1.0, v200
	v_add_f32_e32 v201, 1.0, v201
	v_add_f32_e32 v202, 1.0, v202
	v_add_f32_e32 v203, 1.0, v203
	v_add_f32_e32 v204, 1.0, v204
	v_add_f32_e32 v205, 1.0, v205
	v_add_f32_e32 v206, 1.0, v206
	v_add_f32_e32 v207, 1.0, v207
	v_rcp_f32_e32 v200, v200
	v_rcp_f32_e32 v201, v201
	v_rcp_f32_e32 v202, v202
	v_rcp_f32_e32 v203, v203
	v_rcp_f32_e32 v204, v204
	v_rcp_f32_e32 v205, v205
	v_rcp_f32_e32 v206, v206
	v_rcp_f32_e32 v207, v207
	s_nop 0
	v_mul_f32_e32 v182, v182, v200
	v_mul_f32_e32 v183, v183, v201
	v_mul_f32_e32 v184, v184, v202
	v_mul_f32_e32 v185, v185, v203
	v_mul_f32_e32 v186, v186, v204
	v_mul_f32_e32 v187, v187, v205
	v_mul_f32_e32 v188, v188, v206
	v_mul_f32_e32 v189, v189, v207
	ds_write_b32 v198, v182 offset:32
	ds_write_b32 v198, v183 offset:32800
	ds_write_b32 v198, v184 offset:36
	ds_write_b32 v198, v185 offset:32804
	ds_write_b32 v198, v186 offset:40
	ds_write_b32 v198, v187 offset:32808
	ds_write_b32 v198, v188 offset:44
	ds_write_b32 v198, v189 offset:32812
	s_waitcnt vmcnt(0)
	v_mul_f32_e32 v200, 0xbfb8aa3b, v190
	v_mul_f32_e32 v201, 0xbfb8aa3b, v191
	v_mul_f32_e32 v202, 0xbfb8aa3b, v192
	v_mul_f32_e32 v203, 0xbfb8aa3b, v193
	v_mul_f32_e32 v204, 0xbfb8aa3b, v194
	v_mul_f32_e32 v205, 0xbfb8aa3b, v195
	v_mul_f32_e32 v206, 0xbfb8aa3b, v196
	v_mul_f32_e32 v207, 0xbfb8aa3b, v197
	v_exp_f32_e32 v200, v200
	v_exp_f32_e32 v201, v201
	v_exp_f32_e32 v202, v202
	v_exp_f32_e32 v203, v203
	v_exp_f32_e32 v204, v204
	v_exp_f32_e32 v205, v205
	v_exp_f32_e32 v206, v206
	v_exp_f32_e32 v207, v207
	s_nop 0
	v_add_f32_e32 v200, 1.0, v200
	v_add_f32_e32 v201, 1.0, v201
	v_add_f32_e32 v202, 1.0, v202
	v_add_f32_e32 v203, 1.0, v203
	v_add_f32_e32 v204, 1.0, v204
	v_add_f32_e32 v205, 1.0, v205
	v_add_f32_e32 v206, 1.0, v206
	v_add_f32_e32 v207, 1.0, v207
	v_rcp_f32_e32 v200, v200
	v_rcp_f32_e32 v201, v201
	v_rcp_f32_e32 v202, v202
	v_rcp_f32_e32 v203, v203
	v_rcp_f32_e32 v204, v204
	v_rcp_f32_e32 v205, v205
	v_rcp_f32_e32 v206, v206
	v_rcp_f32_e32 v207, v207
	s_nop 0
	v_mul_f32_e32 v190, v190, v200
	v_mul_f32_e32 v191, v191, v201
	v_mul_f32_e32 v192, v192, v202
	v_mul_f32_e32 v193, v193, v203
	v_mul_f32_e32 v194, v194, v204
	v_mul_f32_e32 v195, v195, v205
	v_mul_f32_e32 v196, v196, v206
	v_mul_f32_e32 v197, v197, v207
	ds_write_b32 v198, v190 offset:48
	ds_write_b32 v198, v191 offset:32816
	ds_write_b32 v198, v192 offset:52
	ds_write_b32 v198, v193 offset:32820
	ds_write_b32 v198, v194 offset:56
	ds_write_b32 v198, v195 offset:32824
	ds_write_b32 v198, v196 offset:60
	ds_write_b32 v198, v197 offset:32828

.LBB0_272:
	s_add_u32 s6, s4, 0x186a0000
	s_addc_u32 s7, s5, 0
	s_lshl_b32 s2, s2, 5
	s_mov_b64 s[8:9], 0x80
	s_and_b32 s14, s2, 0x60
	s_add_i32 m0, s21, 0x18000
	v_lshl_add_u64 v[6:7], v[6:7], 0, s[8:9]
	s_lshl_b32 s13, s12, 13
	s_lshl_b32 s15, s14, 7
	global_load_lds_dwordx4 v[6:7], off
	v_lshl_add_u64 v[4:5], v[4:5], 0, s[8:9]
	s_add_i32 m0, s21, 0x1a000
	s_add_i32 s39, s21, 0x8000
	s_add_i32 s40, s21, 0xa000
	global_load_lds_dwordx4 v[4:5], off
	v_lshl_add_u64 v[0:1], v[0:1], 0, s[8:9]
	s_mov_b32 m0, s39
	s_add_u32 s4, s24, 0x40080
	global_load_lds_dwordx4 v[0:1], off
	v_lshl_add_u64 v[0:1], v[2:3], 0, s[8:9]
	s_mov_b32 m0, s40
	s_addc_u32 s5, s25, 0
	global_load_lds_dwordx4 v[0:1], off
	s_add_i32 m0, s21, 0x1c000
	v_lshl_add_u64 v[0:1], s[4:5], 0, v[132:133]
	global_load_lds_dwordx4 v[0:1], off
	v_lshl_add_u64 v[0:1], s[4:5], 0, v[128:129]
	s_add_i32 m0, s21, 0x1e000
	s_cmpk_lt_u32 s11, 0x100
	global_load_lds_dwordx4 v[0:1], off
	s_waitcnt vmcnt(8)
	s_barrier
	v_lshrrev_b32_e32 v1, 1, v8
	v_and_b32_e32 v1, 24, v1
	v_and_b32_e32 v0, 15, v8
	v_lshlrev_b32_e32 v2, 1, v1
	v_lshl_or_b32 v146, s12, 6, v0
	v_lshl_or_b32 v0, v0, 6, v2
	v_lshlrev_b32_e32 v2, 2, v8
	v_and_b32_e32 v2, 32, v2
	v_bitop3_b32 v3, v0, s13, v2 bitop3:0xde
	v_bitop3_b32 v147, v0, s15, v2 bitop3:0xde
	v_lshlrev_b32_e32 v0, 14, v13
	v_and_b32_e32 v0, 0xffff8000, v0
	v_or_b32_e32 v148, s14, v1
	v_lshl_add_u32 v0, v12, 11, v0
	v_and_b32_e32 v1, 1, v13
	v_lshl_or_b32 v0, v1, 6, v0
	v_lshl_add_u32 v136, v14, 1, v0
	v_lshlrev_b32_e32 v0, 14, v9
	v_and_b32_e32 v0, 0xffff8000, v0
	s_waitcnt vmcnt(6)
	v_lshl_add_u32 v0, v10, 11, v0
	v_and_b32_e32 v1, 1, v9
	s_sext_i32_i16 s2, s10
	s_cselect_b64 s[10:11], -1, 0
	v_lshl_or_b32 v0, v1, 6, v0
	s_add_i32 s43, 0, 0x10000
	s_add_i32 s44, 0, 0x14000
	s_ashr_i32 s41, s90, 31
	s_mov_b32 s42, s90
	v_mov_b32_e32 v137, v133
	v_lshl_add_u32 v138, v11, 1, v0
	v_mov_b32_e32 v139, v133
	v_mov_b64_e32 v[140:141], 0x1600
	v_mov_b64_e32 v[142:143], 0x15ff
	v_add_u32_e32 v149, s43, v147
	v_add_u32_e32 v150, s44, v147
	v_add_u32_e32 v151, 0, v3
	s_movk_i32 s45, 0x1600
	s_barrier
	s_branch .LBB0_275

.LBB0_344:
	s_add_u32 s52, s10, 0x3012000
	s_addc_u32 s53, s11, 0
	s_lshl_b32 s7, s7, 5
	s_mov_b64 s[10:11], 0x80
	s_and_b32 s19, s7, 0x60
	s_add_i32 m0, s46, 0x18000
	v_lshl_add_u64 v[6:7], v[6:7], 0, s[10:11]
	s_lshl_b32 s18, s5, 13
	s_lshl_b32 s7, s19, 7
	global_load_lds_dwordx4 v[6:7], off
	v_lshl_add_u64 v[4:5], v[4:5], 0, s[10:11]
	s_add_i32 m0, s46, 0x1a000
	s_add_i32 s54, s46, 0x8000
	s_add_i32 s55, s46, 0xa000
	global_load_lds_dwordx4 v[4:5], off
	v_lshl_add_u64 v[0:1], v[0:1], 0, s[10:11]
	s_mov_b32 m0, s54
	s_add_u32 s16, s36, 0xb0080
	global_load_lds_dwordx4 v[0:1], off
	v_lshl_add_u64 v[0:1], v[2:3], 0, s[10:11]
	s_mov_b32 m0, s55
	s_addc_u32 s17, s37, 0
	global_load_lds_dwordx4 v[0:1], off
	s_add_i32 m0, s46, 0x1c000
	v_lshl_add_u64 v[0:1], s[16:17], 0, v[176:177]
	global_load_lds_dwordx4 v[0:1], off
	v_lshl_add_u64 v[0:1], s[16:17], 0, v[178:179]
	s_add_i32 m0, s46, 0x1e000
	s_cmpk_lt_u32 s2, 0x100
	global_load_lds_dwordx4 v[0:1], off
	s_waitcnt vmcnt(8)
	s_barrier
	v_bfe_u32 v0, v8, 4, 2
	v_and_b32_e32 v1, 15, v8
	v_lshlrev_b32_e32 v2, 4, v0
	v_lshl_or_b32 v221, s5, 6, v1
	v_lshl_or_b32 v1, v1, 6, v2
	v_lshlrev_b32_e32 v2, 2, v8
	v_and_b32_e32 v2, 32, v2
	v_bitop3_b32 v3, v1, s18, v2 bitop3:0xde
	v_bitop3_b32 v222, v1, s7, v2 bitop3:0xde
	v_lshl_or_b32 v223, v0, 2, s19
	v_lshrrev_b32_e32 v1, 1, v9
	v_mul_lo_u32 v0, v11, s4
	s_mov_b32 s2, 0xb000
	v_mad_u64_u32 v[0:1], s[18:19], v1, s2, v[0:1]
	v_or_b32_e32 v0, v0, v10
	s_sext_i32_i8 s70, s6
	s_mov_b64 s[6:7], 0xb0080
	v_add_lshl_u32 v0, v0, v12, 1
	v_mov_b32_e32 v1, v177
	v_lshl_add_u64 v[180:181], v[0:1], 0, s[6:7]
	v_lshrrev_b32_e32 v1, 1, v13
	v_mul_lo_u32 v0, v14, s4
	v_mad_u64_u32 v[0:1], s[4:5], v1, s2, v[0:1]
	s_waitcnt vmcnt(6)
	v_or_b32_e32 v0, v0, v15
	s_cselect_b64 s[16:17], -1, 0
	v_add_lshl_u32 v0, v0, v16, 1
	v_mov_b32_e32 v1, v177
	s_add_i32 s59, 0, 0x10000
	s_add_i32 s60, 0, 0x14000
	s_ashr_i32 s57, s90, 31
	s_mov_b32 s58, s90
	v_lshl_add_u64 v[182:183], v[0:1], 0, s[6:7]
	v_mov_b64_e32 v[184:185], 0x400
	v_mov_b64_e32 v[186:187], 0x3ff
	v_add_u32_e32 v224, s59, v222
	v_add_u32_e32 v225, s60, v222
	v_add_u32_e32 v226, 0, v3
	s_mov_b32 s61, 0x20000
	s_mov_b32 s62, 0x30000
	s_mov_b32 s63, 0x80000
	s_mov_b32 s64, 0x90000
	s_mov_b32 s65, 0xa0000
	s_mov_b32 s66, 0xb0000
	s_mov_b64 s[18:19], 0x10000
	s_mov_b64 s[20:21], 0x20000
	s_mov_b64 s[22:23], 0x30000
	s_mov_b64 s[24:25], 0x80000
	s_mov_b64 s[26:27], 0x90000
	s_mov_b64 s[28:29], 0xa0000
	s_barrier
	s_branch .LBB0_347

.LBB0_485:
	s_add_u32 s8, s6, 0x186a0000
	s_addc_u32 s9, s7, 0
	s_add_u32 s10, s6, 0x3aa0000
	s_mov_b64 s[12:13], 0x80
	s_addc_u32 s11, s7, 0
	s_and_b32 s34, s4, 3
	s_add_i32 m0, s39, 0x18000
	v_lshl_add_u64 v[6:7], v[6:7], 0, s[12:13]
	s_lshl_b32 s4, s5, 13
	s_lshl_b32 s16, s34, 12
	global_load_lds_dwordx4 v[6:7], off
	v_lshl_add_u64 v[4:5], v[4:5], 0, s[12:13]
	s_add_i32 m0, s39, 0x1a000
	s_add_i32 s64, s39, 0x8000
	s_add_i32 s65, s39, 0xa000
	global_load_lds_dwordx4 v[4:5], off
	v_lshl_add_u64 v[0:1], v[0:1], 0, s[12:13]
	s_mov_b32 m0, s64
	s_add_u32 s14, s52, 0x40080
	global_load_lds_dwordx4 v[0:1], off
	v_lshl_add_u64 v[0:1], v[2:3], 0, s[12:13]
	s_mov_b32 m0, s65
	s_addc_u32 s15, s53, 0
	global_load_lds_dwordx4 v[0:1], off
	s_add_i32 m0, s39, 0x1c000
	v_lshl_add_u64 v[0:1], s[14:15], 0, v[130:131]
	global_load_lds_dwordx4 v[0:1], off
	v_lshl_add_u64 v[0:1], s[14:15], 0, v[134:135]
	s_add_i32 m0, s39, 0x1e000
	s_cmpk_lt_u32 s2, 0x100
	global_load_lds_dwordx4 v[0:1], off
	s_waitcnt vmcnt(8)
	s_barrier
	v_bfe_u32 v1, v8, 4, 2
	v_and_b32_e32 v0, 15, v8
	v_lshlrev_b32_e32 v3, 4, v1
	v_lshl_or_b32 v154, s5, 6, v0
	v_lshl_or_b32 v0, v0, 6, v3
	v_lshlrev_b32_e32 v3, 2, v8
	v_and_b32_e32 v3, 32, v3
	v_lshlrev_b32_e32 v2, 3, v1
	v_bitop3_b32 v4, v0, s4, v3 bitop3:0xde
	v_bitop3_b32 v155, v0, s16, v3 bitop3:0xde
	s_cselect_b64 s[14:15], -1, 0
	s_cmp_eq_u32 s34, 0
	v_cmp_ne_u32_e64 s[4:5], 3, v1
	v_lshlrev_b32_e32 v0, 5, v1
	v_mov_b32_e32 v1, v131
	s_cselect_b64 s[16:17], -1, 0
	s_ashr_i32 s66, s90, 31
	s_ashr_i32 s68, s87, 31
	v_lshl_add_u64 v[0:1], s[6:7], 0, v[0:1]
	s_mov_b64 s[18:19], 0x32a0000
	v_lshl_add_u64 v[136:137], v[0:1], 0, s[18:19]
	s_add_u32 s18, s6, 0x3ba0000
	s_addc_u32 s19, s7, 0
	s_add_u32 s20, s6, 0x3ae0000
	s_addc_u32 s21, s7, 0
	s_add_u32 s22, s6, 0x3be0000
	s_addc_u32 s23, s7, 0
	s_add_u32 s24, s6, 0x3b20000
	v_lshlrev_b32_e32 v0, 14, v9
	s_addc_u32 s25, s7, 0
	v_and_b32_e32 v0, 0xffff8000, v0
	s_add_u32 s26, s6, 0x3c20000
	v_lshl_add_u32 v0, v10, 11, v0
	v_and_b32_e32 v1, 1, v9
	s_addc_u32 s27, s7, 0
	v_lshl_or_b32 v0, v1, 6, v0
	s_add_u32 s28, s6, 0x3b60000
	v_lshl_add_u32 v138, v11, 1, v0
	v_lshlrev_b32_e32 v0, 14, v12
	s_addc_u32 s29, s7, 0
	v_and_b32_e32 v0, 0xffff8000, v0
	s_waitcnt vmcnt(6)
	s_add_u32 s30, s6, 0x3c60000
	v_lshl_add_u32 v0, v13, 11, v0
	v_and_b32_e32 v1, 1, v12
	s_addc_u32 s31, s7, 0
	v_lshl_or_b32 v0, v1, 6, v0
	s_add_i32 s70, 0, 0x10000
	s_add_i32 s71, 0, 0x14000
	s_mov_b32 s67, s90
	v_lshl_or_b32 v156, s34, 5, v2
	v_mov_b32_e32 v139, v131
	v_lshl_add_u32 v140, v14, 1, v0
	v_mov_b32_e32 v141, v131
	v_mov_b64_e32 v[142:143], 0x1400
	v_mov_b64_e32 v[144:145], 0x13ff
	s_movk_i32 s69, 0x281
	v_add_u32_e32 v157, s70, v155
	v_add_u32_e32 v158, s71, v155
	v_add_u32_e32 v159, 0, v4
	s_mov_b64 s[34:35], 0x4800
	s_mov_b64 s[36:37], 0x5800
	s_movk_i32 s72, 0x2600
	v_mov_b32_e32 v160, 0x3e38aa3b
	s_barrier
	s_branch .LBB0_488

.LBB0_644:
	s_add_u32 s12, s4, 0x3ea0000
	s_addc_u32 s13, s5, 0
	s_lshl_b32 s14, s14, 5
	s_and_b32 s20, s14, 0x60
	s_lshl_b32 s17, s16, 13
	s_lshl_b32 s21, s20, 7
	s_add_u32 s14, s4, 0x2f10080
	s_addc_u32 s15, s5, 0
	s_add_i32 m0, s39, 0x18000
	v_lshl_add_u64 v[12:13], s[14:15], 0, v[130:131]
	global_load_lds_dwordx4 v[12:13], off
	v_lshl_add_u64 v[12:13], s[14:15], 0, v[134:135]
	s_add_i32 m0, s39, 0x1a000
	s_mov_b64 s[14:15], 0x80
	s_add_i32 s55, s39, 0x8000
	s_add_i32 s57, s39, 0xa000
	global_load_lds_dwordx4 v[12:13], off
	v_lshl_add_u64 v[0:1], v[0:1], 0, s[14:15]
	s_mov_b32 m0, s55
	s_add_u32 s18, s4, 0x2f90080
	global_load_lds_dwordx4 v[0:1], off
	v_lshl_add_u64 v[0:1], v[2:3], 0, s[14:15]
	s_mov_b32 m0, s57
	s_addc_u32 s19, s5, 0
	global_load_lds_dwordx4 v[0:1], off
	s_add_i32 m0, s39, 0x1c000
	v_lshl_add_u64 v[0:1], s[18:19], 0, v[130:131]
	global_load_lds_dwordx4 v[0:1], off
	v_lshl_add_u64 v[0:1], s[18:19], 0, v[134:135]
	s_add_i32 m0, s39, 0x1e000
	s_cmpk_lt_u32 s2, 0x100
	global_load_lds_dwordx4 v[0:1], off
	s_waitcnt vmcnt(8)
	s_barrier
	v_lshrrev_b32_e32 v1, 1, v4
	v_and_b32_e32 v1, 24, v1
	v_and_b32_e32 v0, 15, v4
	v_lshlrev_b32_e32 v2, 1, v1
	v_lshl_or_b32 v147, s16, 6, v0
	v_lshl_or_b32 v0, v0, 6, v2
	v_lshlrev_b32_e32 v2, 2, v4
	v_and_b32_e32 v2, 32, v2
	v_bitop3_b32 v3, v0, s17, v2 bitop3:0xde
	v_bitop3_b32 v148, v0, s21, v2 bitop3:0xde
	v_lshlrev_b32_e32 v0, 15, v5
	v_and_b32_e32 v0, 0xffff0000, v0
	v_or_b32_e32 v149, s20, v1
	v_lshl_add_u32 v0, v6, 12, v0
	v_and_b32_e32 v1, 1, v5
	v_lshl_or_b32 v0, v1, 6, v0
	v_lshl_add_u32 v136, v7, 1, v0
	v_lshlrev_b32_e32 v0, 15, v8
	v_and_b32_e32 v0, 0xffff0000, v0
	s_waitcnt vmcnt(6)
	v_lshl_add_u32 v0, v9, 12, v0
	v_and_b32_e32 v1, 1, v8
	s_cselect_b64 s[16:17], -1, 0
	v_lshl_or_b32 v0, v1, 6, v0
	s_add_i32 s60, 0, 0x10000
	s_add_i32 s61, 0, 0x14000
	s_ashr_i32 s58, s90, 31
	s_mov_b32 s59, s90
	v_mov_b32_e32 v137, v131
	v_lshl_add_u32 v138, v10, 1, v0
	v_mov_b32_e32 v139, v131
	v_add_u32_e32 v150, s60, v148
	v_add_u32_e32 v151, s61, v148
	v_add_u32_e32 v152, 0, v3
	s_mov_b64 s[18:19], 0x10000
	s_mov_b64 s[20:21], 0x12000
	s_mov_b64 s[22:23], 0x14000
	s_mov_b64 s[24:25], 0x16000
	s_mov_b64 s[42:43], s[8:9]
	s_mov_b32 s62, 0
	s_barrier
	s_branch .LBB0_647

.LBB0_1090:
	s_add_u32 s8, s6, 0x86a0000
	s_addc_u32 s9, s7, 0
	s_add_u32 s10, s6, 0x186a0000
	s_addc_u32 s11, s7, 0
	s_lshl_b32 s6, s12, 5
	s_mov_b64 s[12:13], 0x80
	s_and_b32 s17, s6, 0x60
	s_add_i32 m0, s27, 0x18000
	v_lshl_add_u64 v[6:7], v[6:7], 0, s[12:13]
	s_lshl_b32 s16, s15, 13
	s_lshl_b32 s18, s17, 7
	global_load_lds_dwordx4 v[6:7], off
	v_lshl_add_u64 v[4:5], v[4:5], 0, s[12:13]
	s_add_i32 m0, s27, 0x1a000
	s_add_i32 s44, s27, 0x8000
	s_add_i32 s45, s27, 0xa000
	global_load_lds_dwordx4 v[4:5], off
	v_lshl_add_u64 v[0:1], v[0:1], 0, s[12:13]
	s_mov_b32 m0, s44
	s_add_u32 s6, s30, 0x20080
	global_load_lds_dwordx4 v[0:1], off
	v_lshl_add_u64 v[0:1], v[2:3], 0, s[12:13]
	s_mov_b32 m0, s45
	s_addc_u32 s7, s31, 0
	global_load_lds_dwordx4 v[0:1], off
	s_add_i32 m0, s27, 0x1c000
	v_lshl_add_u64 v[0:1], s[6:7], 0, v[130:131]
	global_load_lds_dwordx4 v[0:1], off
	v_lshl_add_u64 v[0:1], s[6:7], 0, v[134:135]
	s_add_i32 m0, s27, 0x1e000
	s_cmpk_lt_u32 s2, 0x100
	global_load_lds_dwordx4 v[0:1], off
	s_waitcnt vmcnt(8)
	s_barrier
	v_lshrrev_b32_e32 v1, 1, v8
	v_and_b32_e32 v1, 24, v1
	v_and_b32_e32 v0, 15, v8
	v_lshlrev_b32_e32 v2, 1, v1
	v_lshl_or_b32 v152, s15, 6, v0
	v_lshl_or_b32 v0, v0, 6, v2
	v_lshlrev_b32_e32 v2, 2, v8
	v_and_b32_e32 v2, 32, v2
	v_bitop3_b32 v3, v0, s16, v2 bitop3:0xde
	v_bitop3_b32 v153, v0, s18, v2 bitop3:0xde
	v_lshlrev_b32_e32 v0, 13, v9
	v_and_b32_e32 v0, 0xffffc000, v0
	v_or_b32_e32 v154, s17, v1
	v_lshl_add_u32 v0, v10, 10, v0
	v_and_b32_e32 v1, 1, v9
	v_lshl_or_b32 v0, v1, 6, v0
	v_lshl_add_u32 v136, v11, 1, v0
	v_lshlrev_b32_e32 v0, 13, v12
	v_and_b32_e32 v0, 0xffffc000, v0
	s_waitcnt vmcnt(6)
	v_lshl_add_u32 v0, v13, 10, v0
	v_and_b32_e32 v1, 1, v12
	s_sext_i32_i8 s51, s14
	s_cselect_b64 s[14:15], -1, 0
	v_lshl_or_b32 v0, v1, 6, v0
	s_add_i32 s48, 0, 0x10000
	s_add_i32 s49, 0, 0x14000
	s_ashr_i32 s46, s90, 31
	s_mov_b32 s47, s90
	v_mov_b32_e32 v137, v131
	v_lshl_add_u32 v138, v14, 1, v0
	v_mov_b32_e32 v139, v131
	v_mov_b64_e32 v[140:141], 0x400
	v_mov_b64_e32 v[142:143], 0x3ff
	v_add_u32_e32 v155, s48, v153
	v_add_u32_e32 v156, s49, v153
	v_add_u32_e32 v157, 0, v3
	s_movk_i32 s50, 0x2600
	s_mov_b64 s[16:17], 0x1600
	s_barrier
	s_branch .LBB0_1093

.LBB0_1114:
	s_add_u32 s8, s6, 0x86a0000
	s_addc_u32 s9, s7, 0
	s_add_u32 s10, s6, 0x186a0000
	s_addc_u32 s11, s7, 0
	s_lshl_b32 s6, s12, 5
	s_mov_b64 s[12:13], 0x80
	s_and_b32 s17, s6, 0x60
	s_add_i32 m0, s27, 0x18000
	v_lshl_add_u64 v[6:7], v[6:7], 0, s[12:13]
	s_lshl_b32 s16, s15, 13
	s_lshl_b32 s18, s17, 7
	global_load_lds_dwordx4 v[6:7], off
	v_lshl_add_u64 v[4:5], v[4:5], 0, s[12:13]
	s_add_i32 m0, s27, 0x1a000
	s_add_i32 s44, s27, 0x8000
	s_add_i32 s45, s27, 0xa000
	global_load_lds_dwordx4 v[4:5], off
	v_lshl_add_u64 v[0:1], v[0:1], 0, s[12:13]
	s_mov_b32 m0, s44
	s_add_u32 s6, s30, 0x20080
	global_load_lds_dwordx4 v[0:1], off
	v_lshl_add_u64 v[0:1], v[2:3], 0, s[12:13]
	s_mov_b32 m0, s45
	s_addc_u32 s7, s31, 0
	global_load_lds_dwordx4 v[0:1], off
	s_add_i32 m0, s27, 0x1c000
	v_lshl_add_u64 v[0:1], s[6:7], 0, v[134:135]
	global_load_lds_dwordx4 v[0:1], off
	v_lshl_add_u64 v[0:1], s[6:7], 0, v[138:139]
	s_add_i32 m0, s27, 0x1e000
	s_cmpk_lt_u32 s2, 0x100
	global_load_lds_dwordx4 v[0:1], off
	s_waitcnt vmcnt(8)
	s_barrier
	v_lshrrev_b32_e32 v1, 1, v8
	v_and_b32_e32 v1, 24, v1
	v_and_b32_e32 v0, 15, v8
	v_lshlrev_b32_e32 v2, 1, v1
	v_lshl_or_b32 v160, s15, 6, v0
	v_lshl_or_b32 v0, v0, 6, v2
	v_lshlrev_b32_e32 v2, 2, v8
	v_and_b32_e32 v2, 32, v2
	v_bitop3_b32 v3, v0, s16, v2 bitop3:0xde
	v_bitop3_b32 v161, v0, s18, v2 bitop3:0xde
	v_lshlrev_b32_e32 v0, 13, v9
	v_and_b32_e32 v0, 0xffffc000, v0
	v_or_b32_e32 v162, s17, v1
	v_lshl_add_u32 v0, v10, 10, v0
	v_and_b32_e32 v1, 1, v9
	v_lshl_or_b32 v0, v1, 6, v0
	v_lshl_add_u32 v140, v11, 1, v0
	v_lshlrev_b32_e32 v0, 13, v12
	v_and_b32_e32 v0, 0xffffc000, v0
	s_waitcnt vmcnt(6)
	v_lshl_add_u32 v0, v13, 10, v0
	v_and_b32_e32 v1, 1, v12
	s_sext_i32_i8 s51, s14
	s_cselect_b64 s[14:15], -1, 0
	v_lshl_or_b32 v0, v1, 6, v0
	s_add_i32 s48, 0, 0x10000
	s_add_i32 s49, 0, 0x14000
	s_ashr_i32 s46, s90, 31
	s_mov_b32 s47, s90
	v_mov_b32_e32 v141, v135
	v_lshl_add_u32 v142, v14, 1, v0
	v_mov_b32_e32 v143, v135
	v_mov_b64_e32 v[144:145], 0x400
	v_mov_b64_e32 v[146:147], 0x3ff
	v_add_u32_e32 v163, s48, v161
	v_add_u32_e32 v164, s49, v161
	v_add_u32_e32 v165, 0, v3
	s_movk_i32 s50, 0x2600
	s_mov_b64 s[16:17], 0x1e00
	s_barrier
	s_branch .LBB0_1117

.LBB0_1190:
	s_add_u32 s58, s10, 0x3015000
	s_addc_u32 s59, s11, 0
	s_lshl_b32 s10, s12, 5
	s_and_b32 s15, s10, 0x60
	s_mov_b64 s[10:11], 0x80
	s_add_i32 m0, s52, 0x18000
	v_lshl_add_u64 v[6:7], v[6:7], 0, s[10:11]
	s_lshl_b32 s14, s7, 13
	s_lshl_b32 s16, s15, 7
	global_load_lds_dwordx4 v[6:7], off
	v_lshl_add_u64 v[4:5], v[4:5], 0, s[10:11]
	s_add_i32 m0, s52, 0x1a000
	s_add_i32 s60, s52, 0x8000
	s_add_i32 s61, s52, 0xa000
	global_load_lds_dwordx4 v[4:5], off
	v_lshl_add_u64 v[0:1], v[0:1], 0, s[10:11]
	s_mov_b32 m0, s60
	s_add_u32 s12, s42, 0x40080
	global_load_lds_dwordx4 v[0:1], off
	v_lshl_add_u64 v[0:1], v[2:3], 0, s[10:11]
	s_mov_b32 m0, s61
	s_addc_u32 s13, s43, 0
	global_load_lds_dwordx4 v[0:1], off
	s_add_i32 m0, s52, 0x1c000
	v_lshl_add_u64 v[0:1], s[12:13], 0, v[168:169]
	global_load_lds_dwordx4 v[0:1], off
	v_lshl_add_u64 v[0:1], s[12:13], 0, v[170:171]
	s_add_i32 m0, s52, 0x1e000
	s_sext_i32_i8 s39, s6
	global_load_lds_dwordx4 v[0:1], off
	s_waitcnt vmcnt(8)
	s_barrier
	v_bfe_u32 v0, v8, 4, 2
	v_lshlrev_b32_e32 v2, 4, v0
	v_lshl_or_b32 v208, v0, 2, s15
	v_lshlrev_b32_e32 v0, 13, v9
	v_and_b32_e32 v1, 15, v8
	v_and_b32_e32 v0, 0x7fffc000, v0
	v_lshl_or_b32 v206, s7, 6, v1
	v_lshl_or_b32 v1, v1, 6, v2
	v_lshlrev_b32_e32 v2, 2, v8
	v_lshl_add_u32 v0, v10, 10, v0
	v_and_b32_e32 v2, 32, v2
	v_or_b32_e32 v0, v0, v11
	v_bitop3_b32 v3, v1, s14, v2 bitop3:0xde
	v_bitop3_b32 v207, v1, s16, v2 bitop3:0xde
	s_mov_b64 s[6:7], 0x40080
	v_add_lshl_u32 v0, v0, v12, 1
	v_mov_b32_e32 v1, v169
	v_lshl_add_u64 v[172:173], v[0:1], 0, s[6:7]
	v_lshlrev_b32_e32 v0, 13, v13
	v_and_b32_e32 v0, 0x7fffc000, v0
	v_lshl_add_u32 v0, v14, 10, v0
	s_waitcnt vmcnt(6)
	s_cmpk_lt_u32 s2, 0x100
	v_or_b32_e32 v0, v0, v15
	s_cselect_b64 s[12:13], -1, 0
	v_add_lshl_u32 v0, v0, v16, 1
	s_add_i32 s64, 0, 0x10000
	s_add_i32 s65, 0, 0x14000
	s_ashr_i32 s62, s90, 31
	s_mov_b32 s63, s90
	v_lshl_add_u64 v[174:175], v[0:1], 0, s[6:7]
	v_mov_b64_e32 v[176:177], 0x400
	v_mov_b64_e32 v[178:179], 0x3ff
	v_add_u32_e32 v209, s64, v207
	v_add_u32_e32 v210, s65, v207
	v_add_u32_e32 v211, 0, v3
	s_mov_b32 s66, 0x20000
	s_mov_b32 s67, 0x30000
	s_mov_b32 s68, 0x80000
	s_mov_b32 s69, 0x90000
	s_mov_b32 s70, 0xa0000
	s_mov_b32 s71, 0xb0000
	s_mov_b64 s[14:15], 0x10000
	s_mov_b64 s[16:17], 0x20000
	s_mov_b64 s[18:19], 0x30000
	s_mov_b64 s[20:21], 0x80000
	s_mov_b64 s[22:23], 0x90000
	s_mov_b64 s[24:25], 0xa0000
	s_mov_b64 s[26:27], 0xb0000
	s_barrier
	s_branch .LBB0_1193

.LBB0_1325:
	s_add_u32 s8, s6, 0x186a0000
	s_addc_u32 s9, s7, 0
	s_lshl_b32 s2, s2, 5
	s_mov_b64 s[10:11], 0x80
	s_and_b32 s16, s2, 0x60
	s_add_i32 m0, s23, 0x18000
	v_lshl_add_u64 v[6:7], v[6:7], 0, s[10:11]
	s_lshl_b32 s15, s14, 13
	s_lshl_b32 s17, s16, 7
	global_load_lds_dwordx4 v[6:7], off
	v_lshl_add_u64 v[4:5], v[4:5], 0, s[10:11]
	s_add_i32 m0, s23, 0x1a000
	s_add_i32 s41, s23, 0x8000
	s_add_i32 s42, s23, 0xa000
	global_load_lds_dwordx4 v[4:5], off
	v_lshl_add_u64 v[0:1], v[0:1], 0, s[10:11]
	s_mov_b32 m0, s41
	s_add_u32 s6, s26, 0x40080
	global_load_lds_dwordx4 v[0:1], off
	v_lshl_add_u64 v[0:1], v[2:3], 0, s[10:11]
	s_mov_b32 m0, s42
	s_addc_u32 s7, s27, 0
	global_load_lds_dwordx4 v[0:1], off
	s_add_i32 m0, s23, 0x1c000
	v_lshl_add_u64 v[0:1], s[6:7], 0, v[132:133]
	global_load_lds_dwordx4 v[0:1], off
	v_lshl_add_u64 v[0:1], s[6:7], 0, v[128:129]
	s_add_i32 m0, s23, 0x1e000
	s_cmpk_lt_u32 s13, 0x100
	global_load_lds_dwordx4 v[0:1], off
	s_waitcnt vmcnt(8)
	s_barrier
	v_lshrrev_b32_e32 v1, 1, v8
	v_and_b32_e32 v1, 24, v1
	v_and_b32_e32 v0, 15, v8
	v_lshlrev_b32_e32 v2, 1, v1
	s_waitcnt vmcnt(0)
	v_lshl_or_b32 v146, s14, 6, v0
	v_lshl_or_b32 v0, v0, 6, v2
	v_lshlrev_b32_e32 v2, 2, v8
	v_and_b32_e32 v2, 32, v2
	v_bitop3_b32 v3, v0, s15, v2 bitop3:0xde
	v_bitop3_b32 v147, v0, s17, v2 bitop3:0xde
	v_lshlrev_b32_e32 v0, 14, v13
	v_and_b32_e32 v0, 0xffff8000, v0
	v_or_b32_e32 v148, s16, v1
	v_lshl_add_u32 v0, v12, 11, v0
	v_and_b32_e32 v1, 1, v13
	v_lshl_or_b32 v0, v1, 6, v0
	v_lshl_add_u32 v136, v14, 1, v0
	v_lshlrev_b32_e32 v0, 14, v9
	v_and_b32_e32 v0, 0xffff8000, v0
	s_waitcnt vmcnt(6)
	v_lshl_add_u32 v0, v10, 11, v0
	v_and_b32_e32 v1, 1, v9
	s_sext_i32_i16 s2, s12
	s_cselect_b64 s[12:13], -1, 0
	v_lshl_or_b32 v0, v1, 6, v0
	s_add_i32 s45, 0, 0x10000
	s_add_i32 s46, 0, 0x14000
	s_ashr_i32 s43, s90, 31
	s_mov_b32 s44, s90
	v_mov_b32_e32 v137, v133
	v_lshl_add_u32 v138, v11, 1, v0
	v_mov_b32_e32 v139, v133
	v_mov_b64_e32 v[140:141], 0x1600
	v_mov_b64_e32 v[142:143], 0x15ff
	v_add_u32_e32 v149, s45, v147
	v_add_u32_e32 v150, s46, v147
	v_add_u32_e32 v151, 0, v3
	s_movk_i32 s47, 0x1600
	s_barrier
	s_branch .LBB0_1328

.LBB0_1397:
	s_add_u32 s50, s10, 0x3018000
	s_addc_u32 s51, s11, 0
	s_lshl_b32 s7, s7, 5
	s_mov_b64 s[10:11], 0x80
	s_and_b32 s17, s7, 0x60
	s_add_i32 m0, s44, 0x18000
	v_lshl_add_u64 v[6:7], v[6:7], 0, s[10:11]
	s_lshl_b32 s16, s5, 13
	s_lshl_b32 s7, s17, 7
	global_load_lds_dwordx4 v[6:7], off
	v_lshl_add_u64 v[4:5], v[4:5], 0, s[10:11]
	s_add_i32 m0, s44, 0x1a000
	s_add_i32 s52, s44, 0x8000
	s_add_i32 s53, s44, 0xa000
	global_load_lds_dwordx4 v[4:5], off
	v_lshl_add_u64 v[0:1], v[0:1], 0, s[10:11]
	s_mov_b32 m0, s52
	s_add_u32 s14, s34, 0xb0080
	global_load_lds_dwordx4 v[0:1], off
	v_lshl_add_u64 v[0:1], v[2:3], 0, s[10:11]
	s_mov_b32 m0, s53
	s_addc_u32 s15, s35, 0
	global_load_lds_dwordx4 v[0:1], off
	s_add_i32 m0, s44, 0x1c000
	v_lshl_add_u64 v[0:1], s[14:15], 0, v[172:173]
	global_load_lds_dwordx4 v[0:1], off
	v_lshl_add_u64 v[0:1], s[14:15], 0, v[174:175]
	s_add_i32 m0, s44, 0x1e000
	s_cmpk_lt_u32 s2, 0x100
	global_load_lds_dwordx4 v[0:1], off
	s_waitcnt vmcnt(8)
	s_barrier
	v_bfe_u32 v0, v8, 4, 2
	v_and_b32_e32 v1, 15, v8
	v_lshlrev_b32_e32 v2, 4, v0
	v_lshl_or_b32 v218, s5, 6, v1
	v_lshl_or_b32 v1, v1, 6, v2
	v_lshlrev_b32_e32 v2, 2, v8
	v_and_b32_e32 v2, 32, v2
	v_bitop3_b32 v3, v1, s16, v2 bitop3:0xde
	v_bitop3_b32 v219, v1, s7, v2 bitop3:0xde
	v_lshl_or_b32 v220, v0, 2, s17
	v_lshrrev_b32_e32 v1, 1, v9
	v_mul_lo_u32 v0, v11, s4
	s_mov_b32 s2, 0xb000
	v_mad_u64_u32 v[0:1], s[16:17], v1, s2, v[0:1]
	v_or_b32_e32 v0, v0, v10
	s_sext_i32_i8 s67, s6
	s_mov_b64 s[6:7], 0xb0080
	v_add_lshl_u32 v0, v0, v12, 1
	v_mov_b32_e32 v1, v173
	v_lshl_add_u64 v[176:177], v[0:1], 0, s[6:7]
	v_lshrrev_b32_e32 v1, 1, v13
	v_mul_lo_u32 v0, v14, s4
	v_mad_u64_u32 v[0:1], s[4:5], v1, s2, v[0:1]
	s_waitcnt vmcnt(6)
	v_or_b32_e32 v0, v0, v15
	s_cselect_b64 s[14:15], -1, 0
	v_add_lshl_u32 v0, v0, v16, 1
	v_mov_b32_e32 v1, v173
	s_add_i32 s56, 0, 0x10000
	s_add_i32 s57, 0, 0x14000
	s_ashr_i32 s54, s90, 31
	s_mov_b32 s55, s90
	v_lshl_add_u64 v[178:179], v[0:1], 0, s[6:7]
	v_mov_b64_e32 v[180:181], 0x400
	v_mov_b64_e32 v[182:183], 0x3ff
	v_add_u32_e32 v221, s56, v219
	v_add_u32_e32 v222, s57, v219
	v_add_u32_e32 v223, 0, v3
	s_mov_b32 s58, 0x20000
	s_mov_b32 s59, 0x30000
	s_mov_b32 s60, 0x80000
	s_mov_b32 s61, 0x90000
	s_mov_b32 s62, 0xa0000
	s_mov_b32 s63, 0xb0000
	s_mov_b64 s[16:17], 0x10000
	s_mov_b64 s[18:19], 0x20000
	s_mov_b64 s[20:21], 0x30000
	s_mov_b64 s[22:23], 0x80000
	s_mov_b64 s[24:25], 0x90000
	s_mov_b64 s[26:27], 0xa0000
	s_barrier
	s_branch .LBB0_1400
